# attention stagger shortened to 12 sleep units
# baseline (speedup 1.0000x reference)
; __global__ void __launch_bounds__(512, 2) fwd_mega(Args args) {
;     ...
;             for (;;) {
;                 __syncthreads();
;                 if (tid == 0) *qslot = (int)atomicAdd(ctr + 16 + l * 8 + (bx & 7), 1u);
;                 __syncthreads();
;                 const int v = *qslot;
;                 if (v >= 68) break;
;                 int ln = threadIdx.x & 63; asm volatile("" : "+v"(ln));
;                 const int xg = bx & 7;
;                 int b = 0, c = 0, s = -1;
;                 if (v < 48) { b = 2 * xg + v / 24; c = 8 + v % 24; }
;                 else if (v < 56) { const int k = v - 48; c = 7 - (k >> 1); b = 2 * xg + (k & 1); }
;                 else if (v < 60) { s = 4 * xg + (v - 56); }
;                 else { const int k = v - 60; c = 3 - (k >> 1); b = 2 * xg + (k & 1); }
.LBB0_538:
	s_or_b64 exec, exec, s[2:3]
	v_mov_b32_e32 v0, s77
	s_waitcnt lgkmcnt(0)
	s_barrier
	ds_read_b32 v0, v0
	s_movk_i32 s2, 0x43
	s_waitcnt lgkmcnt(0)
	v_cmp_lt_i32_e32 vcc, s2, v0
	v_readfirstlane_b32 s4, v0
	s_mov_b64 s[2:3], -1
	s_cbranch_vccnz .LBB0_533
	v_and_b32_e32 v212, 63, v191
	v_readfirstlane_b32 s98, v191
	s_nop 3
	s_cmp_lt_u32 s98, 0x100
	s_cbranch_scc1 .Lattn_nostag
	s_sleep 12
